# local seams: verdict cached in LDS after the first evaluation, arrival = one returning atomic (generation derived from it), the XCD's last arriver releases without waiting
# speedup vs baseline: 1.0037x; 1.0025x over previous
; __device__ __forceinline__ unsigned xb_ld(unsigned* p)              { return __hip_atomic_load(p, __ATOMIC_RELAXED, __HIP_MEMORY_SCOPE_AGENT); }
; __device__ __forceinline__ unsigned xb_add(unsigned* p, unsigned v) { return __hip_atomic_fetch_add(p, v, __ATOMIC_RELAXED, __HIP_MEMORY_SCOPE_AGENT); }
; #define XB_SPIN(cond, bar) do { unsigned _sp = 0; while (cond) { __builtin_amdgcn_s_sleep(1); \
;     if ((++_sp & 255u) == 0u) { if (xb_ld(&(bar)[XB_TMO])) break; if (_sp > XB_SPIN_CAP) { atomicAdd(&(bar)[XB_TMO], 1u); break; } } } } while (0)
; __device__ __forceinline__ void xcd_barrier(const XcdBarrier& b) {
;     asm volatile("s_waitcnt vmcnt(0)" ::: "memory");
;     __syncthreads();
;     if (threadIdx.x == 0) {
;         unsigned* bar = b.bar;
;         __builtin_amdgcn_s_waitcnt(0);
;         unsigned nloc = b.st[0], nx = b.st[1];
;         if (nloc == 0u) { xcd_barrier_complete(bar, b.x, nloc, nx); b.st[0] = nloc; b.st[1] = nx; }
;         const unsigned old = xb_add(&bar[XB_XSUB(b.x)], 1u);
;         const unsigned gen = old / nloc;
;         if (old + 1u == (gen + 1u) * nloc) {
;             __builtin_amdgcn_fence(__ATOMIC_RELEASE, "agent");
;             asm volatile("s_waitcnt vmcnt(0)" ::: "memory");
;             const unsigned og = xb_add(&bar[XB_TOP], 1u);
;             const unsigned tg = og / nx;
;             if (og + 1u == (tg + 1u) * nx) xb_add(&bar[XB_TOPGEN], 1u);
;             else XB_SPIN(xb_ld(&bar[XB_TOPGEN]) == tg, bar);
;             __builtin_amdgcn_fence(__ATOMIC_ACQUIRE, "agent");
;             xb_add(&bar[XB_XGEN(b.x)], 1u);
;             asm volatile("s_waitcnt vmcnt(0)" ::: "memory");
;         } else {
;             XB_SPIN(xb_ld(&bar[XB_XGEN(b.x)]) == gen, bar);
.LBB0_1679:
	s_cmp_lt_i32 s57, 5
	s_cbranch_scc1 .LBB0_1733
	s_waitcnt vmcnt(0)
	s_waitcnt vmcnt(0) lgkmcnt(0)
	s_barrier
	s_and_saveexec_b64 s[6:7], s[4:5]
	s_cbranch_execz .LBB0_1732
	buffer_inv sc1
	v_mov_b32_e32 v2, 0x20000
	ds_read_b32 v16, v2 offset:8
	ds_read_b32 v2, v2
	s_lshl_b32 s3, s33, 8
	s_add_u32 s8, s50, s3
	s_addc_u32 s9, s51, 0
	s_waitcnt lgkmcnt(0)
	v_readfirstlane_b32 s10, v16
	v_readfirstlane_b32 s12, v2
	s_nop 1
	s_cmp_eq_u32 s10, 1
	s_cbranch_scc1 .Lseam34_go
	s_cmp_eq_u32 s10, 2
	s_cbranch_scc1 .Lseam34_full
	s_cmp_eq_u32 s12, 0
	s_cbranch_scc1 .Lseam34_full
	v_mov_b32_e32 v0, 0
	global_load_dwordx4 v[6:9], v0, s[50:51] offset:256 sc1
	global_load_dwordx4 v[10:13], v0, s[50:51] offset:272 sc1
	s_waitcnt vmcnt(0)
	v_add_u32_e32 v14, -1, v6
	v_and_b32_e32 v1, v14, v6
	v_min_u32_e32 v15, v6, v7
	v_add_u32_e32 v14, -1, v7
	v_and_or_b32 v1, v14, v7, v1
	v_min_u32_e32 v15, v15, v8
	v_add_u32_e32 v14, -1, v8
	v_and_or_b32 v1, v14, v8, v1
	v_min_u32_e32 v15, v15, v9
	v_add_u32_e32 v14, -1, v9
	v_and_or_b32 v1, v14, v9, v1
	v_min_u32_e32 v15, v15, v10
	v_add_u32_e32 v14, -1, v10
	v_and_or_b32 v1, v14, v10, v1
	v_min_u32_e32 v15, v15, v11
	v_add_u32_e32 v14, -1, v11
	v_and_or_b32 v1, v14, v11, v1
	v_min_u32_e32 v15, v15, v12
	v_add_u32_e32 v14, -1, v12
	v_and_or_b32 v1, v14, v12, v1
	v_min_u32_e32 v15, v15, v13
	v_add_u32_e32 v14, -1, v13
	v_and_or_b32 v1, v14, v13, v1
	s_nop 0
	v_readfirstlane_b32 s10, v1
	v_readfirstlane_b32 s13, v15
	s_nop 1
	s_add_i32 s14, s12, -1
	s_and_b32 s14, s14, s12
	s_or_b32 s10, s10, s14
	s_cmp_eq_u32 s13, 0
	s_cselect_b32 s13, 1, 0
	s_or_b32 s10, s10, s13
	s_cmpk_lg_i32 s58, 0x100
	s_cselect_b32 s13, 1, 0
	s_or_b32 s10, s10, s13
	s_cmp_eq_u32 s10, 0
	s_cselect_b32 s10, 1, 2
	v_mov_b32_e32 v16, s10
	v_mov_b32_e32 v2, 0x20000
	ds_write_b32 v2, v16 offset:8
	s_cmp_eq_u32 s10, 2
	s_cbranch_scc1 .Lseam34_full
.Lseam34_go:
	s_ff1_i32_b32 s14, s12
	v_mov_b32_e32 v3, 0x1000
	v_mov_b32_e32 v5, 1
	global_atomic_add v3, v3, v5, s[8:9] offset:1024 sc0
	s_waitcnt vmcnt(0)
	v_readfirstlane_b32 s13, v3
	s_nop 1
	s_lshr_b32 s11, s13, s14
	s_add_i32 s13, s13, 1
	s_add_i32 s15, s12, -1
	s_and_b32 s15, s13, s15
	v_mov_b32_e32 v3, 0x2000
	s_cmp_eq_u32 s15, 0
	s_cbranch_scc1 .Lseam34_lead
.Lseam34_spin:
	s_sleep 1
	global_load_dword v4, v3, s[8:9] offset:1024 sc1
	s_waitcnt vmcnt(0)
	v_readfirstlane_b32 s15, v4
	s_nop 1
	s_cmp_eq_u32 s15, s11
	s_cbranch_scc1 .Lseam34_spin
	s_waitcnt lgkmcnt(0)
	s_branch .LBB0_1732
.Lseam34_lead:
	global_atomic_add v3, v5, s[8:9] offset:1024
	s_waitcnt lgkmcnt(0)
	s_branch .LBB0_1732
.Lseam34_full:
	s_waitcnt lgkmcnt(0)
	s_add_i32 s3, 0, 0x20000
	v_mov_b32_e32 v0, s3
	s_waitcnt vmcnt(0) expcnt(0) lgkmcnt(0)
	ds_read_b32 v2, v0
	s_add_i32 s3, 0, 0x20004
	v_mov_b32_e32 v0, s3
	ds_read_b32 v0, v0
	s_waitcnt lgkmcnt(1)
	v_cmp_ne_u32_e32 vcc, 0, v2
	s_cbranch_vccnz .LBB0_1696
	s_add_u32 s8, s54, 0x3085e00
	s_addc_u32 s9, s55, 0
	s_add_u32 s10, s54, 0x3086000
	s_addc_u32 s11, s55, 0
	s_add_u32 s12, s54, 0x3086100
	s_addc_u32 s13, s55, 0
	s_add_u32 s14, s54, 0x3086200
	s_addc_u32 s15, s55, 0
	s_add_u32 s16, s54, 0x3086300
	s_addc_u32 s17, s55, 0
	s_add_u32 s18, s54, 0x3086400
	s_addc_u32 s19, s55, 0
	s_add_u32 s20, s54, 0x3086500
	s_addc_u32 s21, s55, 0
	s_add_u32 s22, s54, 0x3086600
	s_addc_u32 s23, s55, 0
	s_add_u32 s24, s54, 0x3086700
	s_addc_u32 s25, s55, 0
	s_add_u32 s26, s54, 0x3086800
	s_addc_u32 s27, s55, 0
	s_add_u32 s28, s54, 0x3086900
	s_addc_u32 s29, s55, 0
	s_add_u32 s30, s54, 0x3086a00
	s_addc_u32 s31, s55, 0
	s_add_u32 s34, s54, 0x3086b00
	s_addc_u32 s35, s55, 0
	s_add_u32 s36, s54, 0x3086c00
	s_addc_u32 s37, s55, 0
	s_add_u32 s38, s54, 0x3086d00
	s_addc_u32 s39, s55, 0
	s_add_u32 s40, s54, 0x3086e00
	s_addc_u32 s41, s55, 0
	s_mul_i32 s3, s59, s96
	s_add_u32 s42, s54, 0x3086f00
	s_mul_i32 s3, s3, s58
	s_addc_u32 s43, s55, 0
	s_mov_b32 s60, 1
	v_mov_b32_e32 v16, 0
	s_branch .LBB0_1684

; __device__ __forceinline__ unsigned xb_add(unsigned* p, unsigned v) { return __hip_atomic_fetch_add(p, v, __ATOMIC_RELAXED, __HIP_MEMORY_SCOPE_AGENT); }
; __device__ __forceinline__ void xcd_barrier(const XcdBarrier& b) {
;     asm volatile("s_waitcnt vmcnt(0)" ::: "memory");
;     __syncthreads();
;     if (threadIdx.x == 0) {
;         unsigned* bar = b.bar;
;         __builtin_amdgcn_s_waitcnt(0);
;         unsigned nloc = b.st[0], nx = b.st[1];
;         if (nloc == 0u) { xcd_barrier_complete(bar, b.x, nloc, nx); b.st[0] = nloc; b.st[1] = nx; }
;         const unsigned old = xb_add(&bar[XB_XSUB(b.x)], 1u);
;         const unsigned gen = old / nloc;
;         if (old + 1u == (gen + 1u) * nloc) {
.LBB0_1779:
	s_cmp_lt_i32 s57, 6
	s_cbranch_scc1 .LBB0_1833
	s_waitcnt vmcnt(0)
	s_waitcnt vmcnt(0) lgkmcnt(0)
	s_barrier
	s_and_saveexec_b64 s[6:7], s[4:5]
	s_cbranch_execz .LBB0_1832
	buffer_inv sc1
	v_mov_b32_e32 v2, 0x20000
	ds_read_b32 v16, v2 offset:8
	ds_read_b32 v2, v2
	s_lshl_b32 s3, s33, 8
	s_add_u32 s8, s50, s3
	s_addc_u32 s9, s51, 0
	s_waitcnt lgkmcnt(0)
	v_readfirstlane_b32 s10, v16
	v_readfirstlane_b32 s12, v2
	s_nop 1
	s_cmp_eq_u32 s10, 1
	s_cbranch_scc1 .Lseam45_go
	s_cmp_eq_u32 s10, 2
	s_cbranch_scc1 .Lseam45_full
	s_cmp_eq_u32 s12, 0
	s_cbranch_scc1 .Lseam45_full
	v_mov_b32_e32 v0, 0
	global_load_dwordx4 v[6:9], v0, s[50:51] offset:256 sc1
	global_load_dwordx4 v[10:13], v0, s[50:51] offset:272 sc1
	s_waitcnt vmcnt(0)
	v_add_u32_e32 v14, -1, v6
	v_and_b32_e32 v1, v14, v6
	v_min_u32_e32 v15, v6, v7
	v_add_u32_e32 v14, -1, v7
	v_and_or_b32 v1, v14, v7, v1
	v_min_u32_e32 v15, v15, v8
	v_add_u32_e32 v14, -1, v8
	v_and_or_b32 v1, v14, v8, v1
	v_min_u32_e32 v15, v15, v9
	v_add_u32_e32 v14, -1, v9
	v_and_or_b32 v1, v14, v9, v1
	v_min_u32_e32 v15, v15, v10
	v_add_u32_e32 v14, -1, v10
	v_and_or_b32 v1, v14, v10, v1
	v_min_u32_e32 v15, v15, v11
	v_add_u32_e32 v14, -1, v11
	v_and_or_b32 v1, v14, v11, v1
	v_min_u32_e32 v15, v15, v12
	v_add_u32_e32 v14, -1, v12
	v_and_or_b32 v1, v14, v12, v1
	v_min_u32_e32 v15, v15, v13
	v_add_u32_e32 v14, -1, v13
	v_and_or_b32 v1, v14, v13, v1
	s_nop 0
	v_readfirstlane_b32 s10, v1
	v_readfirstlane_b32 s13, v15
	s_nop 1
	s_add_i32 s14, s12, -1
	s_and_b32 s14, s14, s12
	s_or_b32 s10, s10, s14
	s_cmp_eq_u32 s13, 0
	s_cselect_b32 s13, 1, 0
	s_or_b32 s10, s10, s13
	s_cmpk_lg_i32 s58, 0x100
	s_cselect_b32 s13, 1, 0
	s_or_b32 s10, s10, s13
	s_cmp_eq_u32 s10, 0
	s_cselect_b32 s10, 1, 2
	v_mov_b32_e32 v16, s10
	v_mov_b32_e32 v2, 0x20000
	ds_write_b32 v2, v16 offset:8
	s_cmp_eq_u32 s10, 2
	s_cbranch_scc1 .Lseam45_full

; __device__ __forceinline__ unsigned xb_add(unsigned* p, unsigned v) { return __hip_atomic_fetch_add(p, v, __ATOMIC_RELAXED, __HIP_MEMORY_SCOPE_AGENT); }
; __device__ __forceinline__ void xcd_barrier(const XcdBarrier& b) {
;     asm volatile("s_waitcnt vmcnt(0)" ::: "memory");
;     __syncthreads();
;     if (threadIdx.x == 0) {
;         unsigned* bar = b.bar;
;         __builtin_amdgcn_s_waitcnt(0);
;         unsigned nloc = b.st[0], nx = b.st[1];
;         if (nloc == 0u) { xcd_barrier_complete(bar, b.x, nloc, nx); b.st[0] = nloc; b.st[1] = nx; }
;         const unsigned old = xb_add(&bar[XB_XSUB(b.x)], 1u);
;         const unsigned gen = old / nloc;
;         if (old + 1u == (gen + 1u) * nloc) {
.LBB0_1904:
	s_cmp_lt_i32 s57, 7
	s_cbranch_scc1 .LBB0_1958
	s_waitcnt vmcnt(0)
	s_waitcnt lgkmcnt(0)
	s_barrier
	s_and_saveexec_b64 s[6:7], s[4:5]
	s_cbranch_execz .LBB0_1957
	buffer_inv sc1
	v_mov_b32_e32 v2, 0x20000
	ds_read_b32 v16, v2 offset:8
	ds_read_b32 v2, v2
	s_lshl_b32 s3, s33, 8
	s_add_u32 s8, s50, s3
	s_addc_u32 s9, s51, 0
	s_waitcnt lgkmcnt(0)
	v_readfirstlane_b32 s10, v16
	v_readfirstlane_b32 s12, v2
	s_nop 1
	s_cmp_eq_u32 s10, 1
	s_cbranch_scc1 .Lseam56_go
	s_cmp_eq_u32 s10, 2
	s_cbranch_scc1 .Lseam56_full
	s_cmp_eq_u32 s12, 0
	s_cbranch_scc1 .Lseam56_full
	v_mov_b32_e32 v0, 0
	global_load_dwordx4 v[6:9], v0, s[50:51] offset:256 sc1
	global_load_dwordx4 v[10:13], v0, s[50:51] offset:272 sc1
	s_waitcnt vmcnt(0)
	v_add_u32_e32 v14, -1, v6
	v_and_b32_e32 v1, v14, v6
	v_min_u32_e32 v15, v6, v7
	v_add_u32_e32 v14, -1, v7
	v_and_or_b32 v1, v14, v7, v1
	v_min_u32_e32 v15, v15, v8
	v_add_u32_e32 v14, -1, v8
	v_and_or_b32 v1, v14, v8, v1
	v_min_u32_e32 v15, v15, v9
	v_add_u32_e32 v14, -1, v9
	v_and_or_b32 v1, v14, v9, v1
	v_min_u32_e32 v15, v15, v10
	v_add_u32_e32 v14, -1, v10
	v_and_or_b32 v1, v14, v10, v1
	v_min_u32_e32 v15, v15, v11
	v_add_u32_e32 v14, -1, v11
	v_and_or_b32 v1, v14, v11, v1
	v_min_u32_e32 v15, v15, v12
	v_add_u32_e32 v14, -1, v12
	v_and_or_b32 v1, v14, v12, v1
	v_min_u32_e32 v15, v15, v13
	v_add_u32_e32 v14, -1, v13
	v_and_or_b32 v1, v14, v13, v1
	s_nop 0
	v_readfirstlane_b32 s10, v1
	v_readfirstlane_b32 s13, v15
	s_nop 1
	s_add_i32 s14, s12, -1
	s_and_b32 s14, s14, s12
	s_or_b32 s10, s10, s14
	s_cmp_eq_u32 s13, 0
	s_cselect_b32 s13, 1, 0
	s_or_b32 s10, s10, s13
	s_cmpk_lg_i32 s58, 0x100
	s_cselect_b32 s13, 1, 0
	s_or_b32 s10, s10, s13
	s_cmp_eq_u32 s10, 0
	s_cselect_b32 s10, 1, 2
	v_mov_b32_e32 v16, s10
	v_mov_b32_e32 v2, 0x20000
	ds_write_b32 v2, v16 offset:8
	s_cmp_eq_u32 s10, 2
	s_cbranch_scc1 .Lseam56_full

; __device__ __forceinline__ unsigned xb_add(unsigned* p, unsigned v) { return __hip_atomic_fetch_add(p, v, __ATOMIC_RELAXED, __HIP_MEMORY_SCOPE_AGENT); }
; __device__ __forceinline__ void xcd_barrier(const XcdBarrier& b) {
;     asm volatile("s_waitcnt vmcnt(0)" ::: "memory");
;     __syncthreads();
;     if (threadIdx.x == 0) {
;         unsigned* bar = b.bar;
;         __builtin_amdgcn_s_waitcnt(0);
;         unsigned nloc = b.st[0], nx = b.st[1];
;         if (nloc == 0u) { xcd_barrier_complete(bar, b.x, nloc, nx); b.st[0] = nloc; b.st[1] = nx; }
;         const unsigned old = xb_add(&bar[XB_XSUB(b.x)], 1u);
;         const unsigned gen = old / nloc;
;         if (old + 1u == (gen + 1u) * nloc) {
.LBB0_2222:
	s_cmp_lt_i32 s57, 10
	s_cbranch_scc1 .LBB0_2276
	s_waitcnt vmcnt(0)
	s_barrier
	s_and_saveexec_b64 s[6:7], s[4:5]
	s_cbranch_execz .LBB0_2275
	buffer_inv sc1
	v_mov_b32_e32 v2, 0x20000
	ds_read_b32 v16, v2 offset:8
	ds_read_b32 v2, v2
	s_lshl_b32 s3, s33, 8
	s_add_u32 s8, s50, s3
	s_addc_u32 s9, s51, 0
	s_waitcnt lgkmcnt(0)
	v_readfirstlane_b32 s10, v16
	v_readfirstlane_b32 s12, v2
	s_nop 1
	s_cmp_eq_u32 s10, 1
	s_cbranch_scc1 .Lseam89_go
	s_cmp_eq_u32 s10, 2
	s_cbranch_scc1 .Lseam89_full
	s_cmp_eq_u32 s12, 0
	s_cbranch_scc1 .Lseam89_full
	v_mov_b32_e32 v0, 0
	global_load_dwordx4 v[6:9], v0, s[50:51] offset:256 sc1
	global_load_dwordx4 v[10:13], v0, s[50:51] offset:272 sc1
	s_waitcnt vmcnt(0)
	v_add_u32_e32 v14, -1, v6
	v_and_b32_e32 v1, v14, v6
	v_min_u32_e32 v15, v6, v7
	v_add_u32_e32 v14, -1, v7
	v_and_or_b32 v1, v14, v7, v1
	v_min_u32_e32 v15, v15, v8
	v_add_u32_e32 v14, -1, v8
	v_and_or_b32 v1, v14, v8, v1
	v_min_u32_e32 v15, v15, v9
	v_add_u32_e32 v14, -1, v9
	v_and_or_b32 v1, v14, v9, v1
	v_min_u32_e32 v15, v15, v10
	v_add_u32_e32 v14, -1, v10
	v_and_or_b32 v1, v14, v10, v1
	v_min_u32_e32 v15, v15, v11
	v_add_u32_e32 v14, -1, v11
	v_and_or_b32 v1, v14, v11, v1
	v_min_u32_e32 v15, v15, v12
	v_add_u32_e32 v14, -1, v12
	v_and_or_b32 v1, v14, v12, v1
	v_min_u32_e32 v15, v15, v13
	v_add_u32_e32 v14, -1, v13
	v_and_or_b32 v1, v14, v13, v1
	s_nop 0
	v_readfirstlane_b32 s10, v1
	v_readfirstlane_b32 s13, v15
	s_nop 1
	s_add_i32 s14, s12, -1
	s_and_b32 s14, s14, s12
	s_or_b32 s10, s10, s14
	s_cmp_eq_u32 s13, 0
	s_cselect_b32 s13, 1, 0
	s_or_b32 s10, s10, s13
	s_cmpk_lg_i32 s58, 0x100
	s_cselect_b32 s13, 1, 0
	s_or_b32 s10, s10, s13
	s_cmp_eq_u32 s10, 0
	s_cselect_b32 s10, 1, 2
	v_mov_b32_e32 v16, s10
	v_mov_b32_e32 v2, 0x20000
	ds_write_b32 v2, v16 offset:8
	s_cmp_eq_u32 s10, 2
	s_cbranch_scc1 .Lseam89_full

; __device__ __forceinline__ unsigned xb_ld(unsigned* p)              { return __hip_atomic_load(p, __ATOMIC_RELAXED, __HIP_MEMORY_SCOPE_AGENT); }
; __device__ __forceinline__ void xcd_barrier_complete(unsigned* bar, unsigned x, unsigned& nloc, unsigned& nx) {
;     const unsigned G = gridDim.x * gridDim.y * gridDim.z;
;     unsigned sum, cnt, mine, sp = 0u;
;     for (;;) {
;         sum = 0u; cnt = 0u; mine = 0u;
; #pragma unroll
;         for (unsigned j = 0; j < 16; ++j) { const unsigned c = xb_ld(&bar[XB_XCNT(j)]); sum += c; cnt += (c > 0u) ? 1u : 0u; mine = (j == x) ? c : mine; }
;         if (sum == G) break;
;         __builtin_amdgcn_s_sleep(1);
;         if ((++sp & 255u) == 0u) { if (xb_ld(&bar[XB_TMO])) break; if (sp > XB_SPIN_CAP) { atomicAdd(&bar[XB_TMO], 1u); break; } }
;     }
;     nloc = mine > 0u ? mine : 1u; nx = cnt > 0u ? cnt : 1u;
; }
; __device__ __forceinline__ void xcd_barrier(const XcdBarrier& b) {
;     asm volatile("s_waitcnt vmcnt(0)" ::: "memory");
;     __syncthreads();
;     if (threadIdx.x == 0) {
;         unsigned* bar = b.bar;
;         __builtin_amdgcn_s_waitcnt(0);
;         unsigned nloc = b.st[0], nx = b.st[1];
;         if (nloc == 0u) { xcd_barrier_complete(bar, b.x, nloc, nx); b.st[0] = nloc; b.st[1] = nx; }
.Lseam89_full:
	s_waitcnt lgkmcnt(0)
	s_add_i32 s3, 0, 0x20000
	s_waitcnt vmcnt(7)
	v_mov_b32_e32 v0, s3
	s_waitcnt vmcnt(0) expcnt(0) lgkmcnt(0)
	ds_read_b32 v2, v0
	s_add_i32 s3, 0, 0x20004
	v_mov_b32_e32 v0, s3
	ds_read_b32 v0, v0
	s_waitcnt lgkmcnt(1)
	v_cmp_ne_u32_e32 vcc, 0, v2
	s_cbranch_vccnz .LBB0_2239
	s_add_u32 s8, s54, 0x3085e00
	s_addc_u32 s9, s55, 0
	s_add_u32 s10, s54, 0x3086000
	s_addc_u32 s11, s55, 0
	s_add_u32 s12, s54, 0x3086100
	s_addc_u32 s13, s55, 0
	s_add_u32 s14, s54, 0x3086200
	s_addc_u32 s15, s55, 0
	s_add_u32 s16, s54, 0x3086300
	s_addc_u32 s17, s55, 0
	s_add_u32 s18, s54, 0x3086400
	s_addc_u32 s19, s55, 0
	s_add_u32 s20, s54, 0x3086500
	s_addc_u32 s21, s55, 0
	s_add_u32 s22, s54, 0x3086600
	s_addc_u32 s23, s55, 0
	s_add_u32 s24, s54, 0x3086700
	s_addc_u32 s25, s55, 0
	s_add_u32 s26, s54, 0x3086800
	s_addc_u32 s27, s55, 0
	s_add_u32 s28, s54, 0x3086900
	s_addc_u32 s29, s55, 0
	s_add_u32 s30, s54, 0x3086a00
	s_addc_u32 s31, s55, 0
	s_add_u32 s34, s54, 0x3086b00
	s_addc_u32 s35, s55, 0
	s_add_u32 s36, s54, 0x3086c00
	s_addc_u32 s37, s55, 0
	s_add_u32 s38, s54, 0x3086d00
	s_addc_u32 s39, s55, 0
	s_add_u32 s40, s54, 0x3086e00
	s_addc_u32 s41, s55, 0
	s_mul_i32 s3, s59, s96
	s_add_u32 s42, s54, 0x3086f00
	s_mul_i32 s3, s3, s58
	s_addc_u32 s43, s55, 0
	s_mov_b32 s60, 1
	v_mov_b32_e32 v16, 0
	s_branch .LBB0_2227

; __device__ __forceinline__ unsigned xb_add(unsigned* p, unsigned v) { return __hip_atomic_fetch_add(p, v, __ATOMIC_RELAXED, __HIP_MEMORY_SCOPE_AGENT); }
; __device__ __forceinline__ void xcd_barrier(const XcdBarrier& b) {
;     asm volatile("s_waitcnt vmcnt(0)" ::: "memory");
;     __syncthreads();
;     if (threadIdx.x == 0) {
;         unsigned* bar = b.bar;
;         __builtin_amdgcn_s_waitcnt(0);
;         unsigned nloc = b.st[0], nx = b.st[1];
;         if (nloc == 0u) { xcd_barrier_complete(bar, b.x, nloc, nx); b.st[0] = nloc; b.st[1] = nx; }
;         const unsigned old = xb_add(&bar[XB_XSUB(b.x)], 1u);
;         const unsigned gen = old / nloc;
;         if (old + 1u == (gen + 1u) * nloc) {
.LBB0_2546:
	s_cmp_lt_i32 s57, 13
	s_cbranch_scc1 .LBB0_2600
	s_waitcnt vmcnt(0)
	s_waitcnt lgkmcnt(0)
	s_barrier
	s_and_saveexec_b64 s[6:7], s[4:5]
	s_cbranch_execz .LBB0_2599
	buffer_inv sc1
	v_mov_b32_e32 v2, 0x20000
	ds_read_b32 v16, v2 offset:8
	ds_read_b32 v2, v2
	s_lshl_b32 s3, s33, 8
	s_add_u32 s8, s50, s3
	s_addc_u32 s9, s51, 0
	s_waitcnt lgkmcnt(0)
	v_readfirstlane_b32 s10, v16
	v_readfirstlane_b32 s12, v2
	s_nop 1
	s_cmp_eq_u32 s10, 1
	s_cbranch_scc1 .Lseam1112_go
	s_cmp_eq_u32 s10, 2
	s_cbranch_scc1 .Lseam1112_full
	s_cmp_eq_u32 s12, 0
	s_cbranch_scc1 .Lseam1112_full
	v_mov_b32_e32 v0, 0
	global_load_dwordx4 v[6:9], v0, s[50:51] offset:256 sc1
	global_load_dwordx4 v[10:13], v0, s[50:51] offset:272 sc1
	s_waitcnt vmcnt(0)
	v_add_u32_e32 v14, -1, v6
	v_and_b32_e32 v1, v14, v6
	v_min_u32_e32 v15, v6, v7
	v_add_u32_e32 v14, -1, v7
	v_and_or_b32 v1, v14, v7, v1
	v_min_u32_e32 v15, v15, v8
	v_add_u32_e32 v14, -1, v8
	v_and_or_b32 v1, v14, v8, v1
	v_min_u32_e32 v15, v15, v9
	v_add_u32_e32 v14, -1, v9
	v_and_or_b32 v1, v14, v9, v1
	v_min_u32_e32 v15, v15, v10
	v_add_u32_e32 v14, -1, v10
	v_and_or_b32 v1, v14, v10, v1
	v_min_u32_e32 v15, v15, v11
	v_add_u32_e32 v14, -1, v11
	v_and_or_b32 v1, v14, v11, v1
	v_min_u32_e32 v15, v15, v12
	v_add_u32_e32 v14, -1, v12
	v_and_or_b32 v1, v14, v12, v1
	v_min_u32_e32 v15, v15, v13
	v_add_u32_e32 v14, -1, v13
	v_and_or_b32 v1, v14, v13, v1
	s_nop 0
	v_readfirstlane_b32 s10, v1
	v_readfirstlane_b32 s13, v15
	s_nop 1
	s_add_i32 s14, s12, -1
	s_and_b32 s14, s14, s12
	s_or_b32 s10, s10, s14
	s_cmp_eq_u32 s13, 0
	s_cselect_b32 s13, 1, 0
	s_or_b32 s10, s10, s13
	s_cmpk_lg_i32 s58, 0x100
	s_cselect_b32 s13, 1, 0
	s_or_b32 s10, s10, s13
	s_cmp_eq_u32 s10, 0
	s_cselect_b32 s10, 1, 2
	v_mov_b32_e32 v16, s10
	v_mov_b32_e32 v2, 0x20000
	ds_write_b32 v2, v16 offset:8
	s_cmp_eq_u32 s10, 2
	s_cbranch_scc1 .Lseam1112_full
